# v44 + in-proj K-loop re-cut to 8 barrier intervals per iteration (32 MFMA per segment, merged load segments)
# speedup vs baseline: 1.0013x; 1.0013x over previous
.LBB0_95:
	v_add_u32_e32 v145, 0x10000, v142
	ds_read_b128 v[146:149], v145
	ds_read_b128 v[150:153], v145 offset:1024
	ds_read_b128 v[154:157], v145 offset:2048
	ds_read_b128 v[158:161], v145 offset:3072
	s_add_u32 s16, s14, 0xfff80080
	s_addc_u32 s17, s15, -1
	s_add_i32 s42, 0, 0x10000
	s_cmp_eq_u32 s41, 28
	s_cselect_b32 s19, s9, s17
	s_cselect_b32 s18, s37, s16
	s_cselect_b32 s17, s7, s40
	s_cselect_b32 s16, s38, s39
	s_add_i32 m0, s27, 0xc000
	ds_read_b128 v[162:165], v144
	ds_read_b128 v[166:169], v144 offset:1024
	ds_read_b128 v[170:173], v144 offset:2048
	ds_read_b128 v[174:177], v144 offset:3072
	ds_read_b128 v[178:181], v144 offset:4096
	ds_read_b128 v[182:185], v144 offset:5120
	ds_read_b128 v[186:189], v144 offset:6144
	ds_read_b128 v[190:193], v144 offset:7168
	global_load_lds_dwordx4 v138, s[14:15]
	s_add_i32 m0, s27, 0xe000
	s_nop 0
	global_load_lds_dwordx4 v140, s[14:15]
	s_add_i32 s44, 0, 0x14000
	v_add_u32_e32 v145, s44, v142
	ds_read_b128 v[194:197], v145
	ds_read_b128 v[200:203], v145 offset:1024
	ds_read_b128 v[204:207], v145 offset:2048
	ds_read_b128 v[208:211], v145 offset:3072
	s_setprio 1
	s_barrier
	s_waitcnt lgkmcnt(0)
	v_mfma_f32_16x16x32_bf16 v[128:131], v[146:149], v[162:165], v[128:131]
	v_mfma_f32_16x16x32_bf16 v[128:131], v[150:153], v[166:169], v[128:131]
	v_mfma_f32_16x16x32_bf16 v[120:123], v[150:153], v[174:177], v[120:123]
	v_mfma_f32_16x16x32_bf16 v[120:123], v[146:149], v[170:173], v[120:123]
	v_mfma_f32_16x16x32_bf16 v[104:107], v[146:149], v[178:181], v[104:107]
	v_mfma_f32_16x16x32_bf16 v[104:107], v[150:153], v[182:185], v[104:107]
	v_mfma_f32_16x16x32_bf16 v[88:91], v[150:153], v[190:193], v[88:91]
	v_mfma_f32_16x16x32_bf16 v[88:91], v[146:149], v[186:189], v[88:91]
	v_mfma_f32_16x16x32_bf16 v[84:87], v[154:157], v[186:189], v[84:87]
	v_mfma_f32_16x16x32_bf16 v[84:87], v[158:161], v[190:193], v[84:87]
	v_mfma_f32_16x16x32_bf16 v[100:103], v[158:161], v[182:185], v[100:103]
	v_mfma_f32_16x16x32_bf16 v[100:103], v[154:157], v[178:181], v[100:103]
	v_mfma_f32_16x16x32_bf16 v[116:119], v[154:157], v[170:173], v[116:119]
	v_mfma_f32_16x16x32_bf16 v[116:119], v[158:161], v[174:177], v[116:119]
	v_mfma_f32_16x16x32_bf16 v[124:127], v[158:161], v[166:169], v[124:127]
	v_mfma_f32_16x16x32_bf16 v[124:127], v[154:157], v[162:165], v[124:127]
	v_mfma_f32_16x16x32_bf16 v[112:115], v[194:197], v[162:165], v[112:115]
	v_mfma_f32_16x16x32_bf16 v[112:115], v[200:203], v[166:169], v[112:115]
	v_mfma_f32_16x16x32_bf16 v[96:99], v[200:203], v[174:177], v[96:99]
	v_mfma_f32_16x16x32_bf16 v[96:99], v[194:197], v[170:173], v[96:99]
	v_mfma_f32_16x16x32_bf16 v[80:83], v[194:197], v[178:181], v[80:83]
	v_mfma_f32_16x16x32_bf16 v[80:83], v[200:203], v[182:185], v[80:83]
	v_mfma_f32_16x16x32_bf16 v[72:75], v[200:203], v[190:193], v[72:75]
	v_mfma_f32_16x16x32_bf16 v[72:75], v[194:197], v[186:189], v[72:75]
	v_mfma_f32_16x16x32_bf16 v[68:71], v[204:207], v[186:189], v[68:71]
	v_mfma_f32_16x16x32_bf16 v[68:71], v[208:211], v[190:193], v[68:71]
	v_mfma_f32_16x16x32_bf16 v[76:79], v[208:211], v[182:185], v[76:79]
	v_mfma_f32_16x16x32_bf16 v[76:79], v[204:207], v[178:181], v[76:79]
	v_mfma_f32_16x16x32_bf16 v[92:95], v[204:207], v[170:173], v[92:95]
	v_mfma_f32_16x16x32_bf16 v[92:95], v[208:211], v[174:177], v[92:95]
	v_mfma_f32_16x16x32_bf16 v[108:111], v[208:211], v[166:169], v[108:111]
	s_setprio 0
	v_mfma_f32_16x16x32_bf16 v[108:111], v[204:207], v[162:165], v[108:111]
	s_barrier
	s_mov_b32 m0, s27
	v_lshl_add_u64 v[216:217], s[18:19], 0, v[136:137]
	ds_read_b128 v[162:165], v144 offset:16384
	ds_read_b128 v[166:169], v144 offset:17408
	ds_read_b128 v[170:173], v144 offset:18432
	ds_read_b128 v[174:177], v144 offset:19456
	ds_read_b128 v[178:181], v144 offset:20480
	ds_read_b128 v[182:185], v144 offset:21504
	ds_read_b128 v[186:189], v144 offset:22528
	ds_read_b128 v[190:193], v144 offset:23552
	global_load_lds_dwordx4 v[216:217], off
	v_lshl_add_u64 v[218:219], s[18:19], 0, v[134:135]
	s_mov_b32 m0, s28
	s_nop 0
	global_load_lds_dwordx4 v[218:219], off
	s_add_i32 s42, s42, s26
	v_lshl_add_u64 v[212:213], s[16:17], 0, v[2:3]
	s_mov_b32 m0, s42
	s_nop 0
	global_load_lds_dwordx4 v[212:213], off
	v_lshl_add_u64 v[214:215], s[16:17], 0, v[132:133]
	s_add_i32 m0, s42, 0x2000
	s_nop 0
	global_load_lds_dwordx4 v[214:215], off
	s_add_u32 s42, s16, 0x20000
	s_addc_u32 s43, s17, 0
	s_add_i32 s44, s44, s26
	s_mov_b32 m0, s44
	s_nop 0
	global_load_lds_dwordx4 v2, s[42:43]
	s_add_i32 m0, s44, 0x2000
	s_nop 0
	global_load_lds_dwordx4 v132, s[42:43]
	s_waitcnt vmcnt(6)
	s_setprio 1
	s_barrier
	s_waitcnt lgkmcnt(0)
	v_mfma_f32_16x16x32_bf16 v[64:67], v[146:149], v[162:165], v[64:67]
	v_mfma_f32_16x16x32_bf16 v[64:67], v[150:153], v[166:169], v[64:67]
	v_mfma_f32_16x16x32_bf16 v[56:59], v[150:153], v[174:177], v[56:59]
	v_mfma_f32_16x16x32_bf16 v[56:59], v[146:149], v[170:173], v[56:59]
	v_mfma_f32_16x16x32_bf16 v[40:43], v[146:149], v[178:181], v[40:43]
	v_mfma_f32_16x16x32_bf16 v[40:43], v[150:153], v[182:185], v[40:43]
	v_mfma_f32_16x16x32_bf16 v[24:27], v[150:153], v[190:193], v[24:27]
	v_mfma_f32_16x16x32_bf16 v[24:27], v[146:149], v[186:189], v[24:27]
	v_mfma_f32_16x16x32_bf16 v[20:23], v[154:157], v[186:189], v[20:23]
	v_mfma_f32_16x16x32_bf16 v[20:23], v[158:161], v[190:193], v[20:23]
	v_mfma_f32_16x16x32_bf16 v[36:39], v[158:161], v[182:185], v[36:39]
	v_mfma_f32_16x16x32_bf16 v[36:39], v[154:157], v[178:181], v[36:39]
	v_mfma_f32_16x16x32_bf16 v[52:55], v[154:157], v[170:173], v[52:55]
	v_mfma_f32_16x16x32_bf16 v[52:55], v[158:161], v[174:177], v[52:55]
	v_mfma_f32_16x16x32_bf16 v[60:63], v[158:161], v[166:169], v[60:63]
	v_mfma_f32_16x16x32_bf16 v[60:63], v[154:157], v[162:165], v[60:63]
	v_mfma_f32_16x16x32_bf16 v[48:51], v[194:197], v[162:165], v[48:51]
	v_mfma_f32_16x16x32_bf16 v[48:51], v[200:203], v[166:169], v[48:51]
	v_mfma_f32_16x16x32_bf16 v[32:35], v[200:203], v[174:177], v[32:35]
	v_mfma_f32_16x16x32_bf16 v[32:35], v[194:197], v[170:173], v[32:35]
	v_mfma_f32_16x16x32_bf16 v[16:19], v[194:197], v[178:181], v[16:19]
	v_mfma_f32_16x16x32_bf16 v[16:19], v[200:203], v[182:185], v[16:19]
	v_mfma_f32_16x16x32_bf16 v[8:11], v[200:203], v[190:193], v[8:11]
	v_mfma_f32_16x16x32_bf16 v[8:11], v[194:197], v[186:189], v[8:11]
	v_mfma_f32_16x16x32_bf16 v[4:7], v[204:207], v[186:189], v[4:7]
	v_mfma_f32_16x16x32_bf16 v[4:7], v[208:211], v[190:193], v[4:7]
	v_mfma_f32_16x16x32_bf16 v[12:15], v[208:211], v[182:185], v[12:15]
	v_mfma_f32_16x16x32_bf16 v[12:15], v[204:207], v[178:181], v[12:15]
	v_mfma_f32_16x16x32_bf16 v[28:31], v[204:207], v[170:173], v[28:31]
	v_mfma_f32_16x16x32_bf16 v[28:31], v[208:211], v[174:177], v[28:31]
	v_mfma_f32_16x16x32_bf16 v[44:47], v[208:211], v[166:169], v[44:47]
	s_setprio 0
	v_mfma_f32_16x16x32_bf16 v[44:47], v[204:207], v[162:165], v[44:47]
	s_barrier
	s_add_i32 s42, 0, 0x18000
	v_add_u32_e32 v145, s42, v142
	ds_read_b128 v[146:149], v145
	ds_read_b128 v[150:153], v145 offset:1024
	ds_read_b128 v[154:157], v145 offset:2048
	ds_read_b128 v[158:161], v145 offset:3072
	s_add_u32 s18, s18, 0x80000
	s_addc_u32 s19, s19, 0
	s_mov_b32 m0, s29
	ds_read_b128 v[162:165], v144 offset:32768
	ds_read_b128 v[166:169], v144 offset:33792
	ds_read_b128 v[170:173], v144 offset:34816
	ds_read_b128 v[174:177], v144 offset:35840
	ds_read_b128 v[178:181], v144 offset:36864
	ds_read_b128 v[182:185], v144 offset:37888
	ds_read_b128 v[186:189], v144 offset:38912
	ds_read_b128 v[190:193], v144 offset:39936
	global_load_lds_dwordx4 v136, s[18:19]
	s_mov_b32 m0, s30
	s_nop 0
	global_load_lds_dwordx4 v134, s[18:19]
	s_add_i32 s18, 0, 0x1c000
	v_add_u32_e32 v145, s18, v142
	ds_read_b128 v[194:197], v145
	ds_read_b128 v[200:203], v145 offset:1024
	ds_read_b128 v[204:207], v145 offset:2048
	ds_read_b128 v[208:211], v145 offset:3072
	s_setprio 1
	s_barrier
	s_waitcnt lgkmcnt(0)
	v_mfma_f32_16x16x32_bf16 v[128:131], v[146:149], v[162:165], v[128:131]
	v_mfma_f32_16x16x32_bf16 v[128:131], v[150:153], v[166:169], v[128:131]
	v_mfma_f32_16x16x32_bf16 v[120:123], v[150:153], v[174:177], v[120:123]
	v_mfma_f32_16x16x32_bf16 v[120:123], v[146:149], v[170:173], v[120:123]
	v_mfma_f32_16x16x32_bf16 v[104:107], v[146:149], v[178:181], v[104:107]
	v_mfma_f32_16x16x32_bf16 v[104:107], v[150:153], v[182:185], v[104:107]
	v_mfma_f32_16x16x32_bf16 v[88:91], v[150:153], v[190:193], v[88:91]
	v_mfma_f32_16x16x32_bf16 v[88:91], v[146:149], v[186:189], v[88:91]
	v_mfma_f32_16x16x32_bf16 v[84:87], v[154:157], v[186:189], v[84:87]
	v_mfma_f32_16x16x32_bf16 v[84:87], v[158:161], v[190:193], v[84:87]
	v_mfma_f32_16x16x32_bf16 v[100:103], v[158:161], v[182:185], v[100:103]
	v_mfma_f32_16x16x32_bf16 v[100:103], v[154:157], v[178:181], v[100:103]
	v_mfma_f32_16x16x32_bf16 v[116:119], v[154:157], v[170:173], v[116:119]
	v_mfma_f32_16x16x32_bf16 v[116:119], v[158:161], v[174:177], v[116:119]
	v_mfma_f32_16x16x32_bf16 v[124:127], v[158:161], v[166:169], v[124:127]
	v_mfma_f32_16x16x32_bf16 v[124:127], v[154:157], v[162:165], v[124:127]
	v_mfma_f32_16x16x32_bf16 v[112:115], v[194:197], v[162:165], v[112:115]
	v_mfma_f32_16x16x32_bf16 v[112:115], v[200:203], v[166:169], v[112:115]
	v_mfma_f32_16x16x32_bf16 v[96:99], v[200:203], v[174:177], v[96:99]
	v_mfma_f32_16x16x32_bf16 v[96:99], v[194:197], v[170:173], v[96:99]
	v_mfma_f32_16x16x32_bf16 v[80:83], v[194:197], v[178:181], v[80:83]
	v_mfma_f32_16x16x32_bf16 v[80:83], v[200:203], v[182:185], v[80:83]
	v_mfma_f32_16x16x32_bf16 v[72:75], v[200:203], v[190:193], v[72:75]
	v_mfma_f32_16x16x32_bf16 v[72:75], v[194:197], v[186:189], v[72:75]
	v_mfma_f32_16x16x32_bf16 v[68:71], v[204:207], v[186:189], v[68:71]
	v_mfma_f32_16x16x32_bf16 v[68:71], v[208:211], v[190:193], v[68:71]
	v_mfma_f32_16x16x32_bf16 v[76:79], v[208:211], v[182:185], v[76:79]
	v_mfma_f32_16x16x32_bf16 v[76:79], v[204:207], v[178:181], v[76:79]
	v_mfma_f32_16x16x32_bf16 v[92:95], v[204:207], v[170:173], v[92:95]
	v_mfma_f32_16x16x32_bf16 v[92:95], v[208:211], v[174:177], v[92:95]
	v_mfma_f32_16x16x32_bf16 v[108:111], v[208:211], v[166:169], v[108:111]
	s_setprio 0
	v_mfma_f32_16x16x32_bf16 v[108:111], v[204:207], v[162:165], v[108:111]
	s_barrier
	s_mov_b32 m0, s31
	v_lshl_add_u64 v[220:221], v[216:217], 0, s[2:3]
	ds_read_b128 v[162:165], v144 offset:49152
	ds_read_b128 v[166:169], v144 offset:50176
	ds_read_b128 v[170:173], v144 offset:51200
	ds_read_b128 v[174:177], v144 offset:52224
	ds_read_b128 v[178:181], v144 offset:53248
	ds_read_b128 v[182:185], v144 offset:54272
	ds_read_b128 v[186:189], v144 offset:55296
	ds_read_b128 v[190:193], v144 offset:56320
	global_load_lds_dwordx4 v[220:221], off
	v_lshl_add_u64 v[220:221], v[218:219], 0, s[2:3]
	s_mov_b32 m0, s33
	s_nop 0
	global_load_lds_dwordx4 v[220:221], off
	s_add_i32 s19, s42, s26
	v_lshl_add_u64 v[212:213], v[212:213], 0, s[2:3]
	s_mov_b32 m0, s19
	s_nop 0
	global_load_lds_dwordx4 v[212:213], off
	v_lshl_add_u64 v[212:213], v[214:215], 0, s[2:3]
	s_add_i32 m0, s19, 0x2000
	s_nop 0
	global_load_lds_dwordx4 v[212:213], off
	s_add_u32 s16, s16, 0x20080
	s_addc_u32 s17, s17, 0
	s_add_i32 s18, s18, s26
	s_mov_b32 m0, s18
	s_nop 0
	global_load_lds_dwordx4 v2, s[16:17]
	s_add_i32 m0, s18, 0x2000
	s_nop 0
	global_load_lds_dwordx4 v132, s[16:17]
	s_waitcnt vmcnt(6)
	s_setprio 1
	s_barrier
	s_waitcnt lgkmcnt(0)
	v_mfma_f32_16x16x32_bf16 v[64:67], v[146:149], v[162:165], v[64:67]
	v_mfma_f32_16x16x32_bf16 v[64:67], v[150:153], v[166:169], v[64:67]
	v_mfma_f32_16x16x32_bf16 v[56:59], v[150:153], v[174:177], v[56:59]
	v_mfma_f32_16x16x32_bf16 v[56:59], v[146:149], v[170:173], v[56:59]
	v_mfma_f32_16x16x32_bf16 v[40:43], v[146:149], v[178:181], v[40:43]
	v_mfma_f32_16x16x32_bf16 v[40:43], v[150:153], v[182:185], v[40:43]
	v_mfma_f32_16x16x32_bf16 v[24:27], v[150:153], v[190:193], v[24:27]
	v_mfma_f32_16x16x32_bf16 v[24:27], v[146:149], v[186:189], v[24:27]
	v_mfma_f32_16x16x32_bf16 v[20:23], v[154:157], v[186:189], v[20:23]
	v_mfma_f32_16x16x32_bf16 v[20:23], v[158:161], v[190:193], v[20:23]
	v_mfma_f32_16x16x32_bf16 v[36:39], v[158:161], v[182:185], v[36:39]
	v_mfma_f32_16x16x32_bf16 v[36:39], v[154:157], v[178:181], v[36:39]
	v_mfma_f32_16x16x32_bf16 v[52:55], v[154:157], v[170:173], v[52:55]
	v_mfma_f32_16x16x32_bf16 v[52:55], v[158:161], v[174:177], v[52:55]
	v_mfma_f32_16x16x32_bf16 v[60:63], v[158:161], v[166:169], v[60:63]
	v_mfma_f32_16x16x32_bf16 v[60:63], v[154:157], v[162:165], v[60:63]
	v_mfma_f32_16x16x32_bf16 v[48:51], v[194:197], v[162:165], v[48:51]
	v_mfma_f32_16x16x32_bf16 v[48:51], v[200:203], v[166:169], v[48:51]
	v_mfma_f32_16x16x32_bf16 v[32:35], v[200:203], v[174:177], v[32:35]
	v_mfma_f32_16x16x32_bf16 v[32:35], v[194:197], v[170:173], v[32:35]
	v_mfma_f32_16x16x32_bf16 v[16:19], v[194:197], v[178:181], v[16:19]
	v_mfma_f32_16x16x32_bf16 v[16:19], v[200:203], v[182:185], v[16:19]
	v_mfma_f32_16x16x32_bf16 v[8:11], v[200:203], v[190:193], v[8:11]
	v_mfma_f32_16x16x32_bf16 v[8:11], v[194:197], v[186:189], v[8:11]
	v_mfma_f32_16x16x32_bf16 v[4:7], v[204:207], v[186:189], v[4:7]
	v_mfma_f32_16x16x32_bf16 v[4:7], v[208:211], v[190:193], v[4:7]
	v_mfma_f32_16x16x32_bf16 v[12:15], v[208:211], v[182:185], v[12:15]
	v_mfma_f32_16x16x32_bf16 v[12:15], v[204:207], v[178:181], v[12:15]
	v_mfma_f32_16x16x32_bf16 v[28:31], v[204:207], v[170:173], v[28:31]
	v_mfma_f32_16x16x32_bf16 v[28:31], v[208:211], v[174:177], v[28:31]
	v_mfma_f32_16x16x32_bf16 v[44:47], v[208:211], v[166:169], v[44:47]
	s_setprio 0
	v_mfma_f32_16x16x32_bf16 v[44:47], v[204:207], v[162:165], v[44:47]
	s_barrier
	s_add_i32 s41, s41, 2
	s_add_u32 s14, s14, 0x100
	s_addc_u32 s15, s15, 0
	s_add_u32 s39, s39, 0x100
	s_addc_u32 s40, s40, 0
	s_cmp_gt_u32 s41, 29
	s_cbranch_scc0 .LBB0_95
	v_lshl_add_u32 v145, s36, 8, v1
	v_lshl_or_b32 v202, s35, 8, v143
	v_ashrrev_i32_e32 v203, 31, v202
	v_mov_b64_e32 v[204:205], s[4:5]
	s_mov_b32 s7, 0x8200
	v_cvt_pk_bf16_f32 v72, v72, v73
	v_cvt_pk_bf16_f32 v73, v74, v75
	v_cvt_pk_bf16_f32 v74, v68, v69
	v_add_u32_e32 v68, 0x80, v145
	v_mad_i64_i32 v[206:207], s[14:15], v145, s7, v[204:205]
	v_lshlrev_b64 v[202:203], 1, v[202:203]
	v_cvt_pk_bf16_f32 v112, v112, v113
	v_cvt_pk_bf16_f32 v113, v114, v115
	v_cvt_pk_bf16_f32 v114, v108, v109
	v_or_b32_e32 v108, 16, v145
	v_mad_i64_i32 v[68:69], s[14:15], v68, s7, v[204:205]
	v_cvt_pk_bf16_f32 v48, v48, v49
	v_cvt_pk_bf16_f32 v49, v50, v51
	v_cvt_pk_bf16_f32 v50, v44, v45
	v_add_u32_e32 v44, 0x90, v145
	v_lshl_add_u64 v[206:207], v[206:207], 0, v[202:203]
	v_cvt_pk_bf16_f32 v115, v110, v111
	v_mad_i64_i32 v[108:109], s[14:15], v108, s7, v[204:205]
	v_cvt_pk_bf16_f32 v96, v96, v97
	v_cvt_pk_bf16_f32 v97, v98, v99
	v_cvt_pk_bf16_f32 v98, v92, v93
	v_or_b32_e32 v92, 32, v145
	v_lshl_add_u64 v[68:69], v[68:69], 0, v[202:203]
	v_cvt_pk_bf16_f32 v51, v46, v47
	v_mad_i64_i32 v[44:45], s[14:15], v44, s7, v[204:205]
	v_cvt_pk_bf16_f32 v32, v32, v33
	v_cvt_pk_bf16_f32 v33, v34, v35
	v_cvt_pk_bf16_f32 v34, v28, v29
	v_add_u32_e32 v28, 0xa0, v145
	global_store_dwordx4 v[206:207], v[112:115], off offset:64 nt
	v_cvt_pk_bf16_f32 v99, v94, v95
	v_mad_i64_i32 v[92:93], s[14:15], v92, s7, v[204:205]
	v_lshl_add_u64 v[112:113], v[108:109], 0, v[202:203]
	v_cvt_pk_bf16_f32 v80, v80, v81
	v_cvt_pk_bf16_f32 v81, v82, v83
	v_cvt_pk_bf16_f32 v82, v76, v77
	v_or_b32_e32 v76, 48, v145
	global_store_dwordx4 v[68:69], v[48:51], off offset:64 nt
	v_cvt_pk_bf16_f32 v35, v30, v31
	v_mad_i64_i32 v[28:29], s[14:15], v28, s7, v[204:205]
	v_lshl_add_u64 v[48:49], v[44:45], 0, v[202:203]
	v_cvt_pk_bf16_f32 v16, v16, v17
	v_cvt_pk_bf16_f32 v17, v18, v19
	v_cvt_pk_bf16_f32 v18, v12, v13
	v_add_u32_e32 v12, 0xb0, v145
	global_store_dwordx4 v[112:113], v[96:99], off offset:64 nt
	v_cvt_pk_bf16_f32 v83, v78, v79
	v_mad_i64_i32 v[76:77], s[14:15], v76, s7, v[204:205]
	v_lshl_add_u64 v[96:97], v[92:93], 0, v[202:203]
	global_store_dwordx4 v[48:49], v[32:35], off offset:64 nt
	v_cvt_pk_bf16_f32 v19, v14, v15
	v_mad_i64_i32 v[12:13], s[14:15], v12, s7, v[204:205]
	v_lshl_add_u64 v[32:33], v[28:29], 0, v[202:203]
	v_cvt_pk_bf16_f32 v128, v128, v129
	v_cvt_pk_bf16_f32 v129, v130, v131
	v_cvt_pk_bf16_f32 v130, v124, v125
	v_cvt_pk_bf16_f32 v131, v126, v127
	v_cvt_pk_bf16_f32 v108, v120, v121
	v_cvt_pk_bf16_f32 v109, v122, v123
	v_cvt_pk_bf16_f32 v110, v116, v117
	v_cvt_pk_bf16_f32 v111, v118, v119
	v_cvt_pk_bf16_f32 v92, v104, v105
	v_cvt_pk_bf16_f32 v93, v106, v107
	v_cvt_pk_bf16_f32 v94, v100, v101
	v_cvt_pk_bf16_f32 v95, v102, v103
	global_store_dwordx4 v[96:97], v[80:83], off offset:64 nt
	v_cvt_pk_bf16_f32 v78, v84, v85
	v_cvt_pk_bf16_f32 v79, v86, v87
	v_lshl_add_u64 v[80:81], v[76:77], 0, v[202:203]
	v_cvt_pk_bf16_f32 v76, v88, v89
	v_cvt_pk_bf16_f32 v77, v90, v91
	v_cvt_pk_bf16_f32 v75, v70, v71
	v_cvt_pk_bf16_f32 v64, v64, v65
	v_cvt_pk_bf16_f32 v65, v66, v67
	v_cvt_pk_bf16_f32 v66, v60, v61
	v_cvt_pk_bf16_f32 v67, v62, v63
	v_cvt_pk_bf16_f32 v44, v56, v57
	v_cvt_pk_bf16_f32 v45, v58, v59
	v_cvt_pk_bf16_f32 v46, v52, v53
	v_cvt_pk_bf16_f32 v47, v54, v55
	v_cvt_pk_bf16_f32 v28, v40, v41
	v_cvt_pk_bf16_f32 v29, v42, v43
	v_cvt_pk_bf16_f32 v30, v36, v37
	v_cvt_pk_bf16_f32 v31, v38, v39
	global_store_dwordx4 v[32:33], v[16:19], off offset:64 nt
	v_cvt_pk_bf16_f32 v14, v20, v21
	v_cvt_pk_bf16_f32 v15, v22, v23
	v_lshl_add_u64 v[16:17], v[12:13], 0, v[202:203]
	v_cvt_pk_bf16_f32 v12, v24, v25
	v_cvt_pk_bf16_f32 v13, v26, v27
	v_cvt_pk_bf16_f32 v8, v8, v9
	v_cvt_pk_bf16_f32 v9, v10, v11
	v_cvt_pk_bf16_f32 v10, v4, v5
	v_cvt_pk_bf16_f32 v11, v6, v7
	s_and_b64 vcc, exec, s[0:1]
	s_mov_b32 s35, s6
	s_mov_b32 s36, s8
	s_mov_b64 s[16:17], s[12:13]
	s_mov_b64 s[14:15], s[10:11]
	global_store_dwordx4 v[206:207], v[128:131], off nt
	global_store_dwordx4 v[112:113], v[108:111], off nt
	global_store_dwordx4 v[96:97], v[92:95], off nt
	global_store_dwordx4 v[80:81], v[76:79], off nt
	global_store_dwordx4 v[80:81], v[72:75], off offset:64 nt
	global_store_dwordx4 v[68:69], v[64:67], off nt
	global_store_dwordx4 v[48:49], v[44:47], off nt
	global_store_dwordx4 v[32:33], v[28:31], off nt
	global_store_dwordx4 v[16:17], v[12:15], off nt
	global_store_dwordx4 v[16:17], v[8:11], off offset:64 nt
	s_cbranch_vccz .LBB0_92
	s_waitcnt lgkmcnt(0)
	s_waitcnt vmcnt(0)
	s_cmpk_gt_u32 s21, 0xff
	s_cbranch_scc1 .LBB0_99
	s_barrier
